# stack of the individually neutral K-loop/prologue edits on v26: m0 save/restore trim, merged segment-end waits, K-tile 1 prologue staging ahead of the first wait, plain cached L2-warm load
# baseline (speedup 1.0000x reference)
.LBB0_318:
	ds_read_b128 v[146:149], v194
	ds_read_b128 v[150:153], v194 offset:1024
	ds_read_b128 v[154:157], v194 offset:2048
	ds_read_b128 v[158:161], v194 offset:3072
	ds_read_b128 v[130:133], v194 offset:16384
	ds_read_b128 v[134:137], v194 offset:17408
	ds_read_b128 v[138:141], v194 offset:18432
	ds_read_b128 v[142:145], v194 offset:19456
	s_add_u32 s42, s93, s9
	s_addc_u32 s43, s94, 0
	s_add_u32 s42, s42, 0xffffff80
	s_addc_u32 s43, s43, -1
	s_mov_b32 m0, s65
	s_nop 0
	global_load_lds_dwordx4 v245, s[42:43]
	s_nop 0
	s_mov_b32 m0, s66
	s_nop 0
	global_load_lds_dwordx4 v247, s[42:43]
	s_cmp_eq_u32 s57, s3
	s_cselect_b32 s73, s55, s94
	s_cselect_b32 s72, s54, s93
	s_cselect_b32 s77, s63, s92
	s_cselect_b32 s76, s62, s8
	s_waitcnt lgkmcnt(0)
	ds_read_b128 v[162:165], v252
	ds_read_b128 v[166:169], v252 offset:1024
	ds_read_b128 v[170:173], v252 offset:2048
	ds_read_b128 v[174:177], v252 offset:3072
	ds_read_b128 v[178:181], v252 offset:4096
	ds_read_b128 v[182:185], v252 offset:5120
	ds_read_b128 v[186:189], v252 offset:6144
	ds_read_b128 v[190:193], v252 offset:7168
	s_waitcnt vmcnt(8) lgkmcnt(0)
	s_setprio 1
	s_barrier
	v_mfma_f32_16x16x32_bf16 v[124:127], v[146:149], v[162:165], v[124:127]
	v_mfma_f32_16x16x32_bf16 v[120:123], v[154:157], v[162:165], v[120:123]
	v_mfma_f32_16x16x32_bf16 v[108:111], v[146:149], v[170:173], v[108:111]
	v_mfma_f32_16x16x32_bf16 v[104:107], v[154:157], v[170:173], v[104:107]
	v_mfma_f32_16x16x32_bf16 v[92:95], v[146:149], v[178:181], v[92:95]
	v_mfma_f32_16x16x32_bf16 v[88:91], v[154:157], v[178:181], v[88:91]
	v_mfma_f32_16x16x32_bf16 v[76:79], v[146:149], v[186:189], v[76:79]
	v_mfma_f32_16x16x32_bf16 v[72:75], v[154:157], v[186:189], v[72:75]
	v_mfma_f32_16x16x32_bf16 v[124:127], v[150:153], v[166:169], v[124:127]
	v_mfma_f32_16x16x32_bf16 v[120:123], v[158:161], v[166:169], v[120:123]
	v_mfma_f32_16x16x32_bf16 v[108:111], v[150:153], v[174:177], v[108:111]
	v_mfma_f32_16x16x32_bf16 v[104:107], v[158:161], v[174:177], v[104:107]
	v_mfma_f32_16x16x32_bf16 v[92:95], v[150:153], v[182:185], v[92:95]
	v_mfma_f32_16x16x32_bf16 v[88:91], v[158:161], v[182:185], v[88:91]
	v_mfma_f32_16x16x32_bf16 v[76:79], v[150:153], v[190:193], v[76:79]
	v_mfma_f32_16x16x32_bf16 v[72:75], v[158:161], v[190:193], v[72:75]
	s_setprio 0
	s_setprio 1
	v_mfma_f32_16x16x32_bf16 v[116:119], v[130:133], v[162:165], v[116:119]
	v_mfma_f32_16x16x32_bf16 v[112:115], v[138:141], v[162:165], v[112:115]
	v_mfma_f32_16x16x32_bf16 v[100:103], v[130:133], v[170:173], v[100:103]
	v_mfma_f32_16x16x32_bf16 v[96:99], v[138:141], v[170:173], v[96:99]
	v_mfma_f32_16x16x32_bf16 v[84:87], v[130:133], v[178:181], v[84:87]
	v_mfma_f32_16x16x32_bf16 v[80:83], v[138:141], v[178:181], v[80:83]
	v_mfma_f32_16x16x32_bf16 v[68:71], v[130:133], v[186:189], v[68:71]
	v_mfma_f32_16x16x32_bf16 v[64:67], v[138:141], v[186:189], v[64:67]
	v_mfma_f32_16x16x32_bf16 v[116:119], v[134:137], v[166:169], v[116:119]
	v_mfma_f32_16x16x32_bf16 v[112:115], v[142:145], v[166:169], v[112:115]
	v_mfma_f32_16x16x32_bf16 v[100:103], v[134:137], v[174:177], v[100:103]
	v_mfma_f32_16x16x32_bf16 v[96:99], v[142:145], v[174:177], v[96:99]
	v_mfma_f32_16x16x32_bf16 v[84:87], v[134:137], v[182:185], v[84:87]
	v_mfma_f32_16x16x32_bf16 v[80:83], v[142:145], v[182:185], v[80:83]
	v_mfma_f32_16x16x32_bf16 v[68:71], v[134:137], v[190:193], v[68:71]
	v_mfma_f32_16x16x32_bf16 v[64:67], v[142:145], v[190:193], v[64:67]
	s_setprio 0
	s_barrier
	s_mov_b32 m0, s14
	s_nop 0
	global_load_lds_dwordx4 v246, s[76:77]
	s_add_u32 s74, s76, s9
	s_mov_b32 m0, s15
	s_nop 0
	global_load_lds_dwordx4 v248, s[76:77]
	s_addc_u32 s75, s77, 0
	s_mov_b32 m0, s16
	s_nop 0
	global_load_lds_dwordx4 v246, s[74:75]
	v_cndmask_b32_e64 v128, 0, 1, s[68:69]
	s_mov_b32 m0, s17
	s_nop 0
	global_load_lds_dwordx4 v248, s[74:75]
	s_andn2_b64 vcc, exec, s[68:69]
	s_mov_b32 m0, s11
	s_nop 0
	global_load_lds_dwordx4 v245, s[72:73]
	s_nop 0
	s_mov_b32 m0, s19
	s_nop 0
	global_load_lds_dwordx4 v247, s[72:73]
	ds_read_b128 v[186:189], v252 offset:16384
	ds_read_b128 v[190:193], v252 offset:17408
	ds_read_b128 v[178:181], v252 offset:18432
	ds_read_b128 v[182:185], v252 offset:19456
	ds_read_b128 v[170:173], v252 offset:20480
	ds_read_b128 v[174:177], v252 offset:21504
	ds_read_b128 v[162:165], v252 offset:22528
	ds_read_b128 v[166:169], v252 offset:23552
	v_cmp_ne_u32_e64 s[42:43], 1, v128
	s_waitcnt vmcnt(8) lgkmcnt(0)
	s_barrier
	s_cbranch_vccnz .LBB0_320
	s_setprio 1
	v_mfma_f32_16x16x32_bf16 v[60:63], v[146:149], v[186:189], v[60:63]
	v_mfma_f32_16x16x32_bf16 v[56:59], v[154:157], v[186:189], v[56:59]
	v_mfma_f32_16x16x32_bf16 v[44:47], v[146:149], v[178:181], v[44:47]
	v_mfma_f32_16x16x32_bf16 v[40:43], v[154:157], v[178:181], v[40:43]
	v_mfma_f32_16x16x32_bf16 v[28:31], v[146:149], v[170:173], v[28:31]
	v_mfma_f32_16x16x32_bf16 v[24:27], v[154:157], v[170:173], v[24:27]
	v_mfma_f32_16x16x32_bf16 v[12:15], v[146:149], v[162:165], v[12:15]
	v_mfma_f32_16x16x32_bf16 v[8:11], v[154:157], v[162:165], v[8:11]
	v_mfma_f32_16x16x32_bf16 v[60:63], v[150:153], v[190:193], v[60:63]
	v_mfma_f32_16x16x32_bf16 v[56:59], v[158:161], v[190:193], v[56:59]
	v_mfma_f32_16x16x32_bf16 v[44:47], v[150:153], v[182:185], v[44:47]
	v_mfma_f32_16x16x32_bf16 v[40:43], v[158:161], v[182:185], v[40:43]
	v_mfma_f32_16x16x32_bf16 v[28:31], v[150:153], v[174:177], v[28:31]
	v_mfma_f32_16x16x32_bf16 v[24:27], v[158:161], v[174:177], v[24:27]
	v_mfma_f32_16x16x32_bf16 v[12:15], v[150:153], v[166:169], v[12:15]
	v_mfma_f32_16x16x32_bf16 v[8:11], v[158:161], v[166:169], v[8:11]
	s_setprio 0
	s_setprio 1
	v_mfma_f32_16x16x32_bf16 v[52:55], v[130:133], v[186:189], v[52:55]
	v_mfma_f32_16x16x32_bf16 v[48:51], v[138:141], v[186:189], v[48:51]
	v_mfma_f32_16x16x32_bf16 v[36:39], v[130:133], v[178:181], v[36:39]
	v_mfma_f32_16x16x32_bf16 v[32:35], v[138:141], v[178:181], v[32:35]
	v_mfma_f32_16x16x32_bf16 v[20:23], v[130:133], v[170:173], v[20:23]
	v_mfma_f32_16x16x32_bf16 v[16:19], v[138:141], v[170:173], v[16:19]
	v_mfma_f32_16x16x32_bf16 v[4:7], v[130:133], v[162:165], v[4:7]
	v_mfma_f32_16x16x32_bf16 v[0:3], v[138:141], v[162:165], v[0:3]
	v_mfma_f32_16x16x32_bf16 v[52:55], v[134:137], v[190:193], v[52:55]
	v_mfma_f32_16x16x32_bf16 v[48:51], v[142:145], v[190:193], v[48:51]
	v_mfma_f32_16x16x32_bf16 v[36:39], v[134:137], v[182:185], v[36:39]
	v_mfma_f32_16x16x32_bf16 v[32:35], v[142:145], v[182:185], v[32:35]
	v_mfma_f32_16x16x32_bf16 v[20:23], v[134:137], v[174:177], v[20:23]
	v_mfma_f32_16x16x32_bf16 v[16:19], v[142:145], v[174:177], v[16:19]
	v_mfma_f32_16x16x32_bf16 v[4:7], v[134:137], v[166:169], v[4:7]
	v_mfma_f32_16x16x32_bf16 v[0:3], v[142:145], v[166:169], v[0:3]
	s_setprio 0
.LBB0_320:
	s_add_u32 s80, s72, 0x80
	s_addc_u32 s81, s73, 0
	s_add_u32 s76, s76, 0x80
	s_addc_u32 s77, s77, 0
	s_barrier
	ds_read_b128 v[146:149], v194 offset:32768
	ds_read_b128 v[150:153], v194 offset:33792
	ds_read_b128 v[154:157], v194 offset:34816
	ds_read_b128 v[158:161], v194 offset:35840
	ds_read_b128 v[130:133], v194 offset:49152
	ds_read_b128 v[134:137], v194 offset:50176
	ds_read_b128 v[138:141], v194 offset:51200
	ds_read_b128 v[142:145], v194 offset:52224
	s_add_u32 s72, s72, s9
	s_addc_u32 s73, s73, 0
	s_mov_b32 m0, s20
	s_nop 0
	global_load_lds_dwordx4 v245, s[72:73]
	s_nop 0
	s_mov_b32 m0, s21
	s_nop 0
	global_load_lds_dwordx4 v247, s[72:73]
	s_waitcnt lgkmcnt(0)
	ds_read_b128 v[162:165], v252 offset:32768
	ds_read_b128 v[166:169], v252 offset:33792
	ds_read_b128 v[170:173], v252 offset:34816
	ds_read_b128 v[174:177], v252 offset:35840
	ds_read_b128 v[178:181], v252 offset:36864
	ds_read_b128 v[182:185], v252 offset:37888
	ds_read_b128 v[186:189], v252 offset:38912
	ds_read_b128 v[190:193], v252 offset:39936
	s_waitcnt vmcnt(8) lgkmcnt(0)
	s_setprio 1
	s_barrier
	v_mfma_f32_16x16x32_bf16 v[124:127], v[146:149], v[162:165], v[124:127]
	v_mfma_f32_16x16x32_bf16 v[120:123], v[154:157], v[162:165], v[120:123]
	v_mfma_f32_16x16x32_bf16 v[108:111], v[146:149], v[170:173], v[108:111]
	v_mfma_f32_16x16x32_bf16 v[104:107], v[154:157], v[170:173], v[104:107]
	v_mfma_f32_16x16x32_bf16 v[92:95], v[146:149], v[178:181], v[92:95]
	v_mfma_f32_16x16x32_bf16 v[88:91], v[154:157], v[178:181], v[88:91]
	v_mfma_f32_16x16x32_bf16 v[76:79], v[146:149], v[186:189], v[76:79]
	v_mfma_f32_16x16x32_bf16 v[72:75], v[154:157], v[186:189], v[72:75]
	v_mfma_f32_16x16x32_bf16 v[124:127], v[150:153], v[166:169], v[124:127]
	v_mfma_f32_16x16x32_bf16 v[120:123], v[158:161], v[166:169], v[120:123]
	v_mfma_f32_16x16x32_bf16 v[108:111], v[150:153], v[174:177], v[108:111]
	v_mfma_f32_16x16x32_bf16 v[104:107], v[158:161], v[174:177], v[104:107]
	v_mfma_f32_16x16x32_bf16 v[92:95], v[150:153], v[182:185], v[92:95]
	v_mfma_f32_16x16x32_bf16 v[88:91], v[158:161], v[182:185], v[88:91]
	v_mfma_f32_16x16x32_bf16 v[76:79], v[150:153], v[190:193], v[76:79]
	v_mfma_f32_16x16x32_bf16 v[72:75], v[158:161], v[190:193], v[72:75]
	s_setprio 0
	s_setprio 1
	v_mfma_f32_16x16x32_bf16 v[116:119], v[130:133], v[162:165], v[116:119]
	v_mfma_f32_16x16x32_bf16 v[112:115], v[138:141], v[162:165], v[112:115]
	v_mfma_f32_16x16x32_bf16 v[100:103], v[130:133], v[170:173], v[100:103]
	v_mfma_f32_16x16x32_bf16 v[96:99], v[138:141], v[170:173], v[96:99]
	v_mfma_f32_16x16x32_bf16 v[84:87], v[130:133], v[178:181], v[84:87]
	v_mfma_f32_16x16x32_bf16 v[80:83], v[138:141], v[178:181], v[80:83]
	v_mfma_f32_16x16x32_bf16 v[68:71], v[130:133], v[186:189], v[68:71]
	v_mfma_f32_16x16x32_bf16 v[64:67], v[138:141], v[186:189], v[64:67]
	v_mfma_f32_16x16x32_bf16 v[116:119], v[134:137], v[166:169], v[116:119]
	v_mfma_f32_16x16x32_bf16 v[112:115], v[142:145], v[166:169], v[112:115]
	v_mfma_f32_16x16x32_bf16 v[100:103], v[134:137], v[174:177], v[100:103]
	v_mfma_f32_16x16x32_bf16 v[96:99], v[142:145], v[174:177], v[96:99]
	v_mfma_f32_16x16x32_bf16 v[84:87], v[134:137], v[182:185], v[84:87]
	v_mfma_f32_16x16x32_bf16 v[80:83], v[142:145], v[182:185], v[80:83]
	v_mfma_f32_16x16x32_bf16 v[68:71], v[134:137], v[190:193], v[68:71]
	v_mfma_f32_16x16x32_bf16 v[64:67], v[142:145], v[190:193], v[64:67]
	s_setprio 0
	s_barrier
	s_mov_b32 m0, s23
	s_nop 0
	global_load_lds_dwordx4 v246, s[76:77]
	s_nop 0
	s_mov_b32 m0, s30
	s_nop 0
	global_load_lds_dwordx4 v248, s[76:77]
	s_add_u32 s72, s74, 0x80
	s_addc_u32 s73, s75, 0
	s_mov_b32 m0, s52
	s_nop 0
	global_load_lds_dwordx4 v246, s[72:73]
	s_and_b64 vcc, exec, s[42:43]
	s_mov_b32 m0, s53
	s_nop 0
	global_load_lds_dwordx4 v248, s[72:73]
	s_mov_b32 m0, s47
	s_nop 0
	global_load_lds_dwordx4 v245, s[80:81]
	s_nop 0
	s_mov_b32 m0, s50
	s_nop 0
	global_load_lds_dwordx4 v247, s[80:81]
	ds_read_b128 v[186:189], v252 offset:49152
	ds_read_b128 v[190:193], v252 offset:50176
	ds_read_b128 v[178:181], v252 offset:51200
	ds_read_b128 v[182:185], v252 offset:52224
	ds_read_b128 v[170:173], v252 offset:53248
	ds_read_b128 v[174:177], v252 offset:54272
	ds_read_b128 v[162:165], v252 offset:55296
	ds_read_b128 v[166:169], v252 offset:56320
	s_waitcnt vmcnt(8) lgkmcnt(0)
	s_barrier
	s_cbranch_vccnz .LBB0_317
	s_setprio 1
	v_mfma_f32_16x16x32_bf16 v[60:63], v[146:149], v[186:189], v[60:63]
	v_mfma_f32_16x16x32_bf16 v[56:59], v[154:157], v[186:189], v[56:59]
	v_mfma_f32_16x16x32_bf16 v[44:47], v[146:149], v[178:181], v[44:47]
	v_mfma_f32_16x16x32_bf16 v[40:43], v[154:157], v[178:181], v[40:43]
	v_mfma_f32_16x16x32_bf16 v[28:31], v[146:149], v[170:173], v[28:31]
	v_mfma_f32_16x16x32_bf16 v[24:27], v[154:157], v[170:173], v[24:27]
	v_mfma_f32_16x16x32_bf16 v[12:15], v[146:149], v[162:165], v[12:15]
	v_mfma_f32_16x16x32_bf16 v[8:11], v[154:157], v[162:165], v[8:11]
	v_mfma_f32_16x16x32_bf16 v[60:63], v[150:153], v[190:193], v[60:63]
	v_mfma_f32_16x16x32_bf16 v[56:59], v[158:161], v[190:193], v[56:59]
	v_mfma_f32_16x16x32_bf16 v[44:47], v[150:153], v[182:185], v[44:47]
	v_mfma_f32_16x16x32_bf16 v[40:43], v[158:161], v[182:185], v[40:43]
	v_mfma_f32_16x16x32_bf16 v[28:31], v[150:153], v[174:177], v[28:31]
	v_mfma_f32_16x16x32_bf16 v[24:27], v[158:161], v[174:177], v[24:27]
	v_mfma_f32_16x16x32_bf16 v[12:15], v[150:153], v[166:169], v[12:15]
	v_mfma_f32_16x16x32_bf16 v[8:11], v[158:161], v[166:169], v[8:11]
	s_setprio 0
	s_setprio 1
	v_mfma_f32_16x16x32_bf16 v[52:55], v[130:133], v[186:189], v[52:55]
	v_mfma_f32_16x16x32_bf16 v[48:51], v[138:141], v[186:189], v[48:51]
	v_mfma_f32_16x16x32_bf16 v[36:39], v[130:133], v[178:181], v[36:39]
	v_mfma_f32_16x16x32_bf16 v[32:35], v[138:141], v[178:181], v[32:35]
	v_mfma_f32_16x16x32_bf16 v[20:23], v[130:133], v[170:173], v[20:23]
	v_mfma_f32_16x16x32_bf16 v[16:19], v[138:141], v[170:173], v[16:19]
	v_mfma_f32_16x16x32_bf16 v[4:7], v[130:133], v[162:165], v[4:7]
	v_mfma_f32_16x16x32_bf16 v[0:3], v[138:141], v[162:165], v[0:3]
	v_mfma_f32_16x16x32_bf16 v[52:55], v[134:137], v[190:193], v[52:55]
	v_mfma_f32_16x16x32_bf16 v[48:51], v[142:145], v[190:193], v[48:51]
	v_mfma_f32_16x16x32_bf16 v[36:39], v[134:137], v[182:185], v[36:39]
	v_mfma_f32_16x16x32_bf16 v[32:35], v[142:145], v[182:185], v[32:35]
	v_mfma_f32_16x16x32_bf16 v[20:23], v[134:137], v[174:177], v[20:23]
	v_mfma_f32_16x16x32_bf16 v[16:19], v[142:145], v[174:177], v[16:19]
	v_mfma_f32_16x16x32_bf16 v[4:7], v[134:137], v[166:169], v[4:7]
	v_mfma_f32_16x16x32_bf16 v[0:3], v[142:145], v[166:169], v[0:3]
	s_setprio 0
	s_branch .LBB0_317

.LBB0_413:
	ds_read_b128 v[146:149], v210
	ds_read_b128 v[150:153], v210 offset:1024
	ds_read_b128 v[154:157], v210 offset:2048
	ds_read_b128 v[158:161], v210 offset:3072
	ds_read_b128 v[130:133], v210 offset:16384
	ds_read_b128 v[134:137], v210 offset:17408
	ds_read_b128 v[138:141], v210 offset:18432
	ds_read_b128 v[142:145], v210 offset:19456
	s_mov_b32 m0, s30
	s_nop 0
	global_load_lds_dwordx4 v195, s[46:47]
	s_nop 0
	s_mov_b32 m0, s14
	s_nop 0
	global_load_lds_dwordx4 v197, s[46:47]
	s_add_u32 s38, s46, 0xfffc0080
	s_addc_u32 s39, s47, -1
	s_cmp_eq_u32 s19, 12
	s_cselect_b32 s75, s27, s39
	s_cselect_b32 s74, s99, s38
	s_cselect_b32 s63, s23, s18
	s_cselect_b32 s62, s3, s8
	s_waitcnt lgkmcnt(0)
	ds_read_b128 v[162:165], v209
	ds_read_b128 v[166:169], v209 offset:1024
	ds_read_b128 v[170:173], v209 offset:2048
	ds_read_b128 v[174:177], v209 offset:3072
	ds_read_b128 v[178:181], v209 offset:4096
	ds_read_b128 v[182:185], v209 offset:5120
	ds_read_b128 v[186:189], v209 offset:6144
	ds_read_b128 v[190:193], v209 offset:7168
	s_waitcnt vmcnt(8) lgkmcnt(0)
	s_setprio 1
	s_barrier
	v_mfma_f32_16x16x32_bf16 v[124:127], v[146:149], v[162:165], v[124:127]
	v_mfma_f32_16x16x32_bf16 v[120:123], v[154:157], v[162:165], v[120:123]
	v_mfma_f32_16x16x32_bf16 v[108:111], v[146:149], v[170:173], v[108:111]
	v_mfma_f32_16x16x32_bf16 v[104:107], v[154:157], v[170:173], v[104:107]
	v_mfma_f32_16x16x32_bf16 v[92:95], v[146:149], v[178:181], v[92:95]
	v_mfma_f32_16x16x32_bf16 v[88:91], v[154:157], v[178:181], v[88:91]
	v_mfma_f32_16x16x32_bf16 v[76:79], v[146:149], v[186:189], v[76:79]
	v_mfma_f32_16x16x32_bf16 v[72:75], v[154:157], v[186:189], v[72:75]
	v_mfma_f32_16x16x32_bf16 v[124:127], v[150:153], v[166:169], v[124:127]
	v_mfma_f32_16x16x32_bf16 v[120:123], v[158:161], v[166:169], v[120:123]
	v_mfma_f32_16x16x32_bf16 v[108:111], v[150:153], v[174:177], v[108:111]
	v_mfma_f32_16x16x32_bf16 v[104:107], v[158:161], v[174:177], v[104:107]
	v_mfma_f32_16x16x32_bf16 v[92:95], v[150:153], v[182:185], v[92:95]
	v_mfma_f32_16x16x32_bf16 v[88:91], v[158:161], v[182:185], v[88:91]
	v_mfma_f32_16x16x32_bf16 v[76:79], v[150:153], v[190:193], v[76:79]
	v_mfma_f32_16x16x32_bf16 v[72:75], v[158:161], v[190:193], v[72:75]
	s_setprio 0
	s_setprio 1
	v_mfma_f32_16x16x32_bf16 v[116:119], v[130:133], v[162:165], v[116:119]
	v_mfma_f32_16x16x32_bf16 v[112:115], v[138:141], v[162:165], v[112:115]
	v_mfma_f32_16x16x32_bf16 v[100:103], v[130:133], v[170:173], v[100:103]
	v_mfma_f32_16x16x32_bf16 v[96:99], v[138:141], v[170:173], v[96:99]
	v_mfma_f32_16x16x32_bf16 v[84:87], v[130:133], v[178:181], v[84:87]
	v_mfma_f32_16x16x32_bf16 v[80:83], v[138:141], v[178:181], v[80:83]
	v_mfma_f32_16x16x32_bf16 v[68:71], v[130:133], v[186:189], v[68:71]
	v_mfma_f32_16x16x32_bf16 v[64:67], v[138:141], v[186:189], v[64:67]
	v_mfma_f32_16x16x32_bf16 v[116:119], v[134:137], v[166:169], v[116:119]
	v_mfma_f32_16x16x32_bf16 v[112:115], v[142:145], v[166:169], v[112:115]
	v_mfma_f32_16x16x32_bf16 v[100:103], v[134:137], v[174:177], v[100:103]
	v_mfma_f32_16x16x32_bf16 v[96:99], v[142:145], v[174:177], v[96:99]
	v_mfma_f32_16x16x32_bf16 v[84:87], v[134:137], v[182:185], v[84:87]
	v_mfma_f32_16x16x32_bf16 v[80:83], v[142:145], v[182:185], v[80:83]
	v_mfma_f32_16x16x32_bf16 v[68:71], v[134:137], v[190:193], v[68:71]
	v_mfma_f32_16x16x32_bf16 v[64:67], v[142:145], v[190:193], v[64:67]
	s_setprio 0
	s_barrier
	s_mov_b32 m0, s67
	s_nop 0
	global_load_lds_dwordx4 v196, s[62:63]
	s_add_u32 s44, s62, 0x40000
	s_mov_b32 m0, s86
	s_nop 0
	global_load_lds_dwordx4 v198, s[62:63]
	s_addc_u32 s45, s63, 0
	s_mov_b32 m0, s87
	s_nop 0
	global_load_lds_dwordx4 v196, s[44:45]
	v_cndmask_b32_e64 v128, 0, 1, s[72:73]
	s_mov_b32 m0, s88
	s_nop 0
	global_load_lds_dwordx4 v198, s[44:45]
	v_cmp_ne_u32_e64 s[44:45], 1, v128
	s_mov_b32 m0, s51
	s_nop 0
	global_load_lds_dwordx4 v195, s[74:75]
	s_andn2_b64 vcc, exec, s[72:73]
	s_mov_b32 m0, s89
	s_nop 0
	global_load_lds_dwordx4 v197, s[74:75]
	ds_read_b128 v[186:189], v209 offset:16384
	ds_read_b128 v[190:193], v209 offset:17408
	ds_read_b128 v[178:181], v209 offset:18432
	ds_read_b128 v[182:185], v209 offset:19456
	ds_read_b128 v[170:173], v209 offset:20480
	ds_read_b128 v[174:177], v209 offset:21504
	ds_read_b128 v[162:165], v209 offset:22528
	ds_read_b128 v[166:169], v209 offset:23552
	s_waitcnt vmcnt(8) lgkmcnt(0)
	s_barrier
	s_cbranch_vccnz .LBB0_415
	s_setprio 1
	v_mfma_f32_16x16x32_bf16 v[60:63], v[146:149], v[186:189], v[60:63]
	v_mfma_f32_16x16x32_bf16 v[56:59], v[154:157], v[186:189], v[56:59]
	v_mfma_f32_16x16x32_bf16 v[44:47], v[146:149], v[178:181], v[44:47]
	v_mfma_f32_16x16x32_bf16 v[40:43], v[154:157], v[178:181], v[40:43]
	v_mfma_f32_16x16x32_bf16 v[28:31], v[146:149], v[170:173], v[28:31]
	v_mfma_f32_16x16x32_bf16 v[24:27], v[154:157], v[170:173], v[24:27]
	v_mfma_f32_16x16x32_bf16 v[12:15], v[146:149], v[162:165], v[12:15]
	v_mfma_f32_16x16x32_bf16 v[8:11], v[154:157], v[162:165], v[8:11]
	v_mfma_f32_16x16x32_bf16 v[60:63], v[150:153], v[190:193], v[60:63]
	v_mfma_f32_16x16x32_bf16 v[56:59], v[158:161], v[190:193], v[56:59]
	v_mfma_f32_16x16x32_bf16 v[44:47], v[150:153], v[182:185], v[44:47]
	v_mfma_f32_16x16x32_bf16 v[40:43], v[158:161], v[182:185], v[40:43]
	v_mfma_f32_16x16x32_bf16 v[28:31], v[150:153], v[174:177], v[28:31]
	v_mfma_f32_16x16x32_bf16 v[24:27], v[158:161], v[174:177], v[24:27]
	v_mfma_f32_16x16x32_bf16 v[12:15], v[150:153], v[166:169], v[12:15]
	v_mfma_f32_16x16x32_bf16 v[8:11], v[158:161], v[166:169], v[8:11]
	s_setprio 0
	s_setprio 1
	v_mfma_f32_16x16x32_bf16 v[52:55], v[130:133], v[186:189], v[52:55]
	v_mfma_f32_16x16x32_bf16 v[48:51], v[138:141], v[186:189], v[48:51]
	v_mfma_f32_16x16x32_bf16 v[36:39], v[130:133], v[178:181], v[36:39]
	v_mfma_f32_16x16x32_bf16 v[32:35], v[138:141], v[178:181], v[32:35]
	v_mfma_f32_16x16x32_bf16 v[20:23], v[130:133], v[170:173], v[20:23]
	v_mfma_f32_16x16x32_bf16 v[16:19], v[138:141], v[170:173], v[16:19]
	v_mfma_f32_16x16x32_bf16 v[4:7], v[130:133], v[162:165], v[4:7]
	v_mfma_f32_16x16x32_bf16 v[0:3], v[138:141], v[162:165], v[0:3]
	v_mfma_f32_16x16x32_bf16 v[52:55], v[134:137], v[190:193], v[52:55]
	v_mfma_f32_16x16x32_bf16 v[48:51], v[142:145], v[190:193], v[48:51]
	v_mfma_f32_16x16x32_bf16 v[36:39], v[134:137], v[182:185], v[36:39]
	v_mfma_f32_16x16x32_bf16 v[32:35], v[142:145], v[182:185], v[32:35]
	v_mfma_f32_16x16x32_bf16 v[20:23], v[134:137], v[174:177], v[20:23]
	v_mfma_f32_16x16x32_bf16 v[16:19], v[142:145], v[174:177], v[16:19]
	v_mfma_f32_16x16x32_bf16 v[4:7], v[134:137], v[166:169], v[4:7]
	v_mfma_f32_16x16x32_bf16 v[0:3], v[142:145], v[166:169], v[0:3]
	s_setprio 0
.LBB0_415:
	s_add_u32 s76, s74, 0x80
	s_addc_u32 s77, s75, 0
	s_add_u32 s38, s62, 0x80
	s_addc_u32 s39, s63, 0
	s_barrier
	ds_read_b128 v[146:149], v210 offset:32768
	ds_read_b128 v[150:153], v210 offset:33792
	ds_read_b128 v[154:157], v210 offset:34816
	ds_read_b128 v[158:161], v210 offset:35840
	ds_read_b128 v[130:133], v210 offset:49152
	ds_read_b128 v[134:137], v210 offset:50176
	ds_read_b128 v[138:141], v210 offset:51200
	ds_read_b128 v[142:145], v210 offset:52224
	s_add_u32 s74, s74, 0x40000
	s_addc_u32 s75, s75, 0
	s_mov_b32 m0, s92
	s_nop 0
	global_load_lds_dwordx4 v195, s[74:75]
	s_nop 0
	s_mov_b32 m0, s93
	s_nop 0
	global_load_lds_dwordx4 v197, s[74:75]
	s_waitcnt lgkmcnt(0)
	ds_read_b128 v[162:165], v209 offset:32768
	ds_read_b128 v[166:169], v209 offset:33792
	ds_read_b128 v[170:173], v209 offset:34816
	ds_read_b128 v[174:177], v209 offset:35840
	ds_read_b128 v[178:181], v209 offset:36864
	ds_read_b128 v[182:185], v209 offset:37888
	ds_read_b128 v[186:189], v209 offset:38912
	ds_read_b128 v[190:193], v209 offset:39936
	s_waitcnt vmcnt(8) lgkmcnt(0)
	s_setprio 1
	s_barrier
	v_mfma_f32_16x16x32_bf16 v[124:127], v[146:149], v[162:165], v[124:127]
	v_mfma_f32_16x16x32_bf16 v[120:123], v[154:157], v[162:165], v[120:123]
	v_mfma_f32_16x16x32_bf16 v[108:111], v[146:149], v[170:173], v[108:111]
	v_mfma_f32_16x16x32_bf16 v[104:107], v[154:157], v[170:173], v[104:107]
	v_mfma_f32_16x16x32_bf16 v[92:95], v[146:149], v[178:181], v[92:95]
	v_mfma_f32_16x16x32_bf16 v[88:91], v[154:157], v[178:181], v[88:91]
	v_mfma_f32_16x16x32_bf16 v[76:79], v[146:149], v[186:189], v[76:79]
	v_mfma_f32_16x16x32_bf16 v[72:75], v[154:157], v[186:189], v[72:75]
	v_mfma_f32_16x16x32_bf16 v[124:127], v[150:153], v[166:169], v[124:127]
	v_mfma_f32_16x16x32_bf16 v[120:123], v[158:161], v[166:169], v[120:123]
	v_mfma_f32_16x16x32_bf16 v[108:111], v[150:153], v[174:177], v[108:111]
	v_mfma_f32_16x16x32_bf16 v[104:107], v[158:161], v[174:177], v[104:107]
	v_mfma_f32_16x16x32_bf16 v[92:95], v[150:153], v[182:185], v[92:95]
	v_mfma_f32_16x16x32_bf16 v[88:91], v[158:161], v[182:185], v[88:91]
	v_mfma_f32_16x16x32_bf16 v[76:79], v[150:153], v[190:193], v[76:79]
	v_mfma_f32_16x16x32_bf16 v[72:75], v[158:161], v[190:193], v[72:75]
	s_setprio 0
	s_setprio 1
	v_mfma_f32_16x16x32_bf16 v[116:119], v[130:133], v[162:165], v[116:119]
	v_mfma_f32_16x16x32_bf16 v[112:115], v[138:141], v[162:165], v[112:115]
	v_mfma_f32_16x16x32_bf16 v[100:103], v[130:133], v[170:173], v[100:103]
	v_mfma_f32_16x16x32_bf16 v[96:99], v[138:141], v[170:173], v[96:99]
	v_mfma_f32_16x16x32_bf16 v[84:87], v[130:133], v[178:181], v[84:87]
	v_mfma_f32_16x16x32_bf16 v[80:83], v[138:141], v[178:181], v[80:83]
	v_mfma_f32_16x16x32_bf16 v[68:71], v[130:133], v[186:189], v[68:71]
	v_mfma_f32_16x16x32_bf16 v[64:67], v[138:141], v[186:189], v[64:67]
	v_mfma_f32_16x16x32_bf16 v[116:119], v[134:137], v[166:169], v[116:119]
	v_mfma_f32_16x16x32_bf16 v[112:115], v[142:145], v[166:169], v[112:115]
	v_mfma_f32_16x16x32_bf16 v[100:103], v[134:137], v[174:177], v[100:103]
	v_mfma_f32_16x16x32_bf16 v[96:99], v[142:145], v[174:177], v[96:99]
	v_mfma_f32_16x16x32_bf16 v[84:87], v[134:137], v[182:185], v[84:87]
	v_mfma_f32_16x16x32_bf16 v[80:83], v[142:145], v[182:185], v[80:83]
	v_mfma_f32_16x16x32_bf16 v[68:71], v[134:137], v[190:193], v[68:71]
	v_mfma_f32_16x16x32_bf16 v[64:67], v[142:145], v[190:193], v[64:67]
	s_setprio 0
	s_barrier
	s_mov_b32 m0, s95
	s_nop 0
	global_load_lds_dwordx4 v196, s[38:39]
	s_nop 0
	s_mov_b32 m0, s96
	s_nop 0
	global_load_lds_dwordx4 v198, s[38:39]
	s_add_u32 s38, s62, 0x40080
	s_addc_u32 s39, s63, 0
	s_mov_b32 m0, s65
	s_nop 0
	global_load_lds_dwordx4 v196, s[38:39]
	s_and_b64 vcc, exec, s[44:45]
	s_mov_b32 m0, s50
	s_nop 0
	global_load_lds_dwordx4 v198, s[38:39]
	s_mov_b32 m0, s97
	s_nop 0
	global_load_lds_dwordx4 v195, s[76:77]
	s_nop 0
	s_mov_b32 m0, s9
	s_nop 0
	global_load_lds_dwordx4 v197, s[76:77]
	ds_read_b128 v[186:189], v209 offset:49152
	ds_read_b128 v[190:193], v209 offset:50176
	ds_read_b128 v[178:181], v209 offset:51200
	ds_read_b128 v[182:185], v209 offset:52224
	ds_read_b128 v[170:173], v209 offset:53248
	ds_read_b128 v[174:177], v209 offset:54272
	ds_read_b128 v[162:165], v209 offset:55296
	ds_read_b128 v[166:169], v209 offset:56320
	s_waitcnt vmcnt(8) lgkmcnt(0)
	s_barrier
	s_cbranch_vccnz .LBB0_412
	s_setprio 1
	v_mfma_f32_16x16x32_bf16 v[60:63], v[146:149], v[186:189], v[60:63]
	v_mfma_f32_16x16x32_bf16 v[56:59], v[154:157], v[186:189], v[56:59]
	v_mfma_f32_16x16x32_bf16 v[44:47], v[146:149], v[178:181], v[44:47]
	v_mfma_f32_16x16x32_bf16 v[40:43], v[154:157], v[178:181], v[40:43]
	v_mfma_f32_16x16x32_bf16 v[28:31], v[146:149], v[170:173], v[28:31]
	v_mfma_f32_16x16x32_bf16 v[24:27], v[154:157], v[170:173], v[24:27]
	v_mfma_f32_16x16x32_bf16 v[12:15], v[146:149], v[162:165], v[12:15]
	v_mfma_f32_16x16x32_bf16 v[8:11], v[154:157], v[162:165], v[8:11]
	v_mfma_f32_16x16x32_bf16 v[60:63], v[150:153], v[190:193], v[60:63]
	v_mfma_f32_16x16x32_bf16 v[56:59], v[158:161], v[190:193], v[56:59]
	v_mfma_f32_16x16x32_bf16 v[44:47], v[150:153], v[182:185], v[44:47]
	v_mfma_f32_16x16x32_bf16 v[40:43], v[158:161], v[182:185], v[40:43]
	v_mfma_f32_16x16x32_bf16 v[28:31], v[150:153], v[174:177], v[28:31]
	v_mfma_f32_16x16x32_bf16 v[24:27], v[158:161], v[174:177], v[24:27]
	v_mfma_f32_16x16x32_bf16 v[12:15], v[150:153], v[166:169], v[12:15]
	v_mfma_f32_16x16x32_bf16 v[8:11], v[158:161], v[166:169], v[8:11]
	s_setprio 0
	s_setprio 1
	v_mfma_f32_16x16x32_bf16 v[52:55], v[130:133], v[186:189], v[52:55]
	v_mfma_f32_16x16x32_bf16 v[48:51], v[138:141], v[186:189], v[48:51]
	v_mfma_f32_16x16x32_bf16 v[36:39], v[130:133], v[178:181], v[36:39]
	v_mfma_f32_16x16x32_bf16 v[32:35], v[138:141], v[178:181], v[32:35]
	v_mfma_f32_16x16x32_bf16 v[20:23], v[130:133], v[170:173], v[20:23]
	v_mfma_f32_16x16x32_bf16 v[16:19], v[138:141], v[170:173], v[16:19]
	v_mfma_f32_16x16x32_bf16 v[4:7], v[130:133], v[162:165], v[4:7]
	v_mfma_f32_16x16x32_bf16 v[0:3], v[138:141], v[162:165], v[0:3]
	v_mfma_f32_16x16x32_bf16 v[52:55], v[134:137], v[190:193], v[52:55]
	v_mfma_f32_16x16x32_bf16 v[48:51], v[142:145], v[190:193], v[48:51]
	v_mfma_f32_16x16x32_bf16 v[36:39], v[134:137], v[182:185], v[36:39]
	v_mfma_f32_16x16x32_bf16 v[32:35], v[142:145], v[182:185], v[32:35]
	v_mfma_f32_16x16x32_bf16 v[20:23], v[134:137], v[174:177], v[20:23]
	v_mfma_f32_16x16x32_bf16 v[16:19], v[142:145], v[174:177], v[16:19]
	v_mfma_f32_16x16x32_bf16 v[4:7], v[134:137], v[166:169], v[4:7]
	v_mfma_f32_16x16x32_bf16 v[0:3], v[142:145], v[166:169], v[0:3]
	s_setprio 0
	s_branch .LBB0_412
